# adds the one-hop grid barrier (non-leader workgroups poll the top-level generation word; leader skips the per-XCD generation bump) on top of the rotated version
# speedup vs baseline: 1.0004x; 1.0004x over previous
.LBB0_1013:
	s_or_b64 exec, exec, s[2:3]
	v_cvt_f32_u32_e32 v4, v2
	s_waitcnt vmcnt(0)
	v_readfirstlane_b32 s2, v3
	v_sub_u32_e32 v3, 0, v2
	v_rcp_iflag_f32_e32 v4, v4
	v_add_u32_e32 v5, s2, v1
	v_mul_f32_e32 v4, 0x4f7ffffe, v4
	v_cvt_u32_f32_e32 v4, v4
	v_mul_lo_u32 v1, v3, v4
	v_mul_hi_u32 v1, v4, v1
	v_add_u32_e32 v1, v4, v1
	v_mul_hi_u32 v1, v5, v1
	v_mul_lo_u32 v3, v1, v2
	v_sub_u32_e32 v3, v5, v3
	v_add_u32_e32 v4, 1, v1
	v_cmp_ge_u32_e32 vcc, v3, v2
	s_nop 1
	v_cndmask_b32_e32 v1, v1, v4, vcc
	v_sub_u32_e32 v4, v3, v2
	v_cndmask_b32_e32 v3, v3, v4, vcc
	v_add_u32_e32 v4, 1, v1
	v_cmp_ge_u32_e32 vcc, v3, v2
	v_add_u32_e32 v3, 1, v5
	s_nop 0
	v_cndmask_b32_e32 v1, v1, v4, vcc
	v_mul_lo_u32 v4, v2, v1
	v_add_u32_e32 v2, v4, v2
	v_cmp_ne_u32_e32 vcc, v3, v2
	s_and_saveexec_b64 s[2:3], vcc
	s_xor_b64 s[2:3], exec, s[2:3]
	s_cbranch_execz .LBB0_1027
	s_waitcnt lgkmcnt(0)
	v_mov_b32_e32 v0, 0
	global_load_dword v2, v0, s[60:61] sc1
	s_waitcnt vmcnt(0)
	v_cmp_eq_u32_e32 vcc, v2, v1
	s_and_saveexec_b64 s[4:5], vcc
	s_cbranch_execz .LBB0_1026
	s_mov_b32 s16, 1
	s_mov_b64 s[6:7], 0
	s_branch .LBB0_1017

.LBB0_1019:
	global_load_dword v2, v0, s[60:61] sc1
	s_add_i32 s16, s16, 1
	s_mov_b64 s[12:13], -1
	s_waitcnt vmcnt(0)
	v_cmp_ne_u32_e32 vcc, v2, v1
	s_orn2_b64 s[10:11], vcc, exec
	s_branch .LBB0_1016
